# DA tile loop: per-tile class-table ds_read hoisted above the DMA-issue block (wait stays at first consumer)
# speedup vs baseline: 1.0055x; 1.0012x over previous
; #define WAIT_BAR_0() asm volatile("s_waitcnt vmcnt(0) lgkmcnt(0)\n\ts_barrier" ::: "memory")
; #define WAIT_BAR_0() asm volatile("s_waitcnt vmcnt(0) lgkmcnt(0)\n\ts_barrier" ::: "memory")
; #define WAIT_BAR_0() asm volatile("s_waitcnt vmcnt(0) lgkmcnt(0)\n\ts_barrier" ::: "memory")
; __device__ __forceinline__ void attn_unit_da(const AttnUnit& U, char* lds) {
;     ...
;   f32x16 p0, p1; float mn = 0.f, al = 1.f; bf16x8 pa0, pa1, pa2, pa3; const int NT = U.NT;
;   DMA_TILE(0, 0);
;   WAIT_BAR_0();
;   for (int j = 0; j < NT; ++j) {
;     const int st = j & 1;
;     if (j + 1 < NT) DMA_TILE(j + 1, st ^ 1);
;     float rc;
;     { const int c_ = __builtin_amdgcn_readfirstlane(cls[j]); const float* ak_ = aux + j * KVBLK;
.LBB0_1938:
	s_and_b32 s40, s36, 1
	v_mov_b32_e32 v153, s39
	ds_read_b32 v153, v153
	s_cmp_gt_u32 s36, 62
	s_cbranch_scc1 .LBB0_1940
	v_mov_b32_e32 v148, v226
	s_add_u32 s4, s0, s25
	s_addc_u32 s5, s1, 0
	v_bfe_u32 v150, v148, 4, 5
	v_and_b32_e32 v0, 15, v148
	v_lshrrev_b32_e32 v149, 4, v148
	v_mul_u32_u24_e32 v146, 0x1800, v150
	s_add_u32 s4, s4, 0xfffff000
	v_lshlrev_b32_e32 v151, 2, v149
	v_bitop3_b32 v0, v151, v0, 12 bitop3:0x6c
	v_lshrrev_b32_e32 v151, 2, v149
	v_bitop3_b32 v0, v151, v0, 3 bitop3:0x6c
	v_lshlrev_b32_e32 v146, 1, v146
	s_addc_u32 s5, s5, -1
	s_lshl_b32 s18, s40, 14
	v_lshl_or_b32 v0, v0, 4, v146
	s_xor_b32 s18, s18, 0x4000
	v_lshl_add_u64 v[146:147], s[4:5], 0, v[0:1]
	v_add_u32_e32 v0, 0x60000, v0
	s_add_i32 s18, s18, s38
	s_mov_b32 s19, m0
	s_mov_b32 m0, s18
	s_nop 0
	global_load_lds_dwordx4 v[146:147], off
	s_mov_b32 m0, s19
	v_lshl_add_u64 v[146:147], s[4:5], 0, v[0:1]
	s_add_i32 s4, s18, 0x2000
	s_mov_b32 s5, m0
	s_mov_b32 m0, s4
	s_nop 0
	global_load_lds_dwordx4 v[146:147], off
	s_mov_b32 m0, s5
	v_lshlrev_b32_e32 v146, 3, v148
	v_and_b32_e32 v152, 24, v146
	v_lshrrev_b32_e32 v146, 1, v148
	v_lshrrev_b32_e32 v147, 5, v148
	v_bfe_u32 v0, v148, 2, 2
	v_and_b32_e32 v146, 8, v146
	v_and_b32_e32 v147, 4, v147
	v_and_b32_e32 v151, 0x60, v148
	v_or3_b32 v148, v147, v0, v146
	v_and_or_b32 v0, v149, 16, v148
	v_mul_u32_u24_e32 v0, 0x1800, v0
	v_or_b32_e32 v150, 32, v150
	s_lshl_b32 s4, s40, 15
	v_or3_b32 v0, v0, v151, v152
	s_xor_b32 s4, s4, 0x8000
	v_lshl_add_u64 v[146:147], v[0:1], 1, s[0:1]
	v_and_or_b32 v0, v150, 48, v148
	s_add_i32 s4, s4, s37
	s_mov_b32 s5, m0
	s_mov_b32 m0, s4
	s_nop 0
	global_load_lds_dwordx4 v[146:147], off
	s_mov_b32 m0, s5
	v_mul_u32_u24_e32 v0, 0x1800, v0
	v_lshl_add_u64 v[146:147], v[146:147], 0, s[22:23]
	s_add_i32 s5, s4, 0x4000
	s_mov_b32 s18, m0
	s_mov_b32 m0, s5
	s_nop 0
	global_load_lds_dwordx4 v[146:147], off
	s_mov_b32 m0, s18
	v_or3_b32 v0, v0, v151, v152
	v_lshl_add_u64 v[146:147], v[0:1], 1, s[0:1]
	s_add_i32 s5, s4, 0x2000
	s_mov_b32 s18, m0
	s_mov_b32 m0, s5
	s_nop 0
	global_load_lds_dwordx4 v[146:147], off
	s_mov_b32 m0, s18
	v_lshl_add_u64 v[146:147], v[146:147], 0, s[22:23]
	s_addk_i32 s4, 0x6000
	s_mov_b32 s5, m0
	s_mov_b32 m0, s4
	s_nop 0
	global_load_lds_dwordx4 v[146:147], off
	s_mov_b32 m0, s5
; __device__ __forceinline__ void attn_unit_da(const AttnUnit& U, char* lds) {
;     ...
;     { const int c_ = __builtin_amdgcn_readfirstlane(cls[j]); const float* ak_ = aux + j * KVBLK;
;       if (c_ < 2) { rc = (c_ == 0) ? pq * U.nsl : -pq * U.nsl;
; #pragma unroll
;         for (int g = 0; g < 4; ++g) { const f32x4 a_ = *(const f32x4*)(ak_ + 8 * g + 4 * hi), b_ = *(const f32x4*)(ak_ + 32 + 8 * g + 4 * hi);
; #pragma unroll
;           for (int e = 0; e < 4; ++e) { p0[4 * g + e] = a_[e]; p1[4 * g + e] = b_[e]; } } }
;       else { rc = 0.f; const int* pg_ = U.posg + j * KVBLK;
; #pragma unroll
;         for (int g = 0; g < 4; ++g)
; #pragma unroll
;           for (int e = 0; e < 4; ++e) { p0[4 * g + e] = fabsf(pq - (float)(pg_[8 * g + 4 * hi + e] - pq0i)) * U.nsl; p1[4 * g + e] = fabsf(pq - (float)(pg_[32 + 8 * g + 4 * hi + e] - pq0i)) * U.nsl; } } }
.LBB0_1940:
	s_mov_b64 s[4:5], -1
	s_waitcnt lgkmcnt(0)
	v_readfirstlane_b32 s18, v153
	s_cmp_gt_i32 s18, 1
	s_cbranch_scc0 .LBB0_1942
	v_lshl_add_u64 v[154:155], v[232:233], 0, s[6:7]
	global_load_dwordx4 v[146:149], v[154:155], off offset:96
	global_load_dwordx4 v[150:153], v[154:155], off offset:64
	v_mov_b32_e32 v229, v228
	s_mov_b64 s[4:5], 0
	s_waitcnt vmcnt(1)
	v_sub_u32_e32 v0, v148, v244
	v_sub_u32_e32 v156, v149, v244
	v_sub_u32_e32 v157, v146, v244
	v_sub_u32_e32 v158, v147, v244
	s_waitcnt vmcnt(0)
	v_sub_u32_e32 v162, v152, v244
	v_sub_u32_e32 v163, v153, v244
	v_sub_u32_e32 v164, v150, v244
	v_sub_u32_e32 v165, v151, v244
	global_load_dwordx4 v[146:149], v[154:155], off offset:32
	global_load_dwordx4 v[150:153], v[154:155], off
	v_cvt_f32_i32_e32 v0, v0
	v_sub_f32_e32 v0, v144, v0
	s_waitcnt vmcnt(1)
	v_sub_u32_e32 v166, v148, v244
	v_sub_u32_e32 v167, v149, v244
	v_sub_u32_e32 v168, v146, v244
	v_sub_u32_e32 v169, v147, v244
	s_waitcnt vmcnt(0)
	v_sub_u32_e32 v170, v152, v244
	v_sub_u32_e32 v171, v153, v244
	v_sub_u32_e32 v172, v150, v244
	v_sub_u32_e32 v173, v151, v244
	global_load_dwordx4 v[146:149], v[154:155], off offset:224
	global_load_dwordx4 v[150:153], v[154:155], off offset:192
	s_waitcnt vmcnt(1)
	v_sub_u32_e32 v174, v148, v244
	v_sub_u32_e32 v175, v149, v244
	v_sub_u32_e32 v176, v146, v244
	v_sub_u32_e32 v177, v147, v244
	s_waitcnt vmcnt(0)
	v_sub_u32_e32 v210, v152, v244
	v_sub_u32_e32 v211, v153, v244
	v_sub_u32_e32 v212, v150, v244
	v_sub_u32_e32 v213, v151, v244
	global_load_dwordx4 v[146:149], v[154:155], off offset:160
	global_load_dwordx4 v[150:153], v[154:155], off offset:128
	s_waitcnt vmcnt(1)
	v_sub_u32_e32 v216, v146, v244
	v_sub_u32_e32 v217, v147, v244
	v_cvt_f32_i32_e32 v146, v157
	v_cvt_f32_i32_e32 v147, v158
	v_sub_u32_e32 v214, v148, v244
	v_cvt_f32_i32_e32 v148, v156
	v_sub_f32_e32 v146, v142, v146
	v_sub_f32_e32 v147, v143, v147
	v_and_b32_e32 v147, 0x7fffffff, v147
	v_and_b32_e32 v146, 0x7fffffff, v146
	v_sub_f32_e32 v148, v145, v148
	v_sub_u32_e32 v215, v149, v244
	v_and_b32_e32 v149, 0x7fffffff, v148
	v_and_b32_e32 v148, 0x7fffffff, v0
	v_pk_mul_f32 v[158:159], v[228:229], v[146:147]
	v_cvt_f32_i32_e32 v0, v162
	v_cvt_f32_i32_e32 v146, v163
	s_waitcnt vmcnt(0)
	v_sub_u32_e32 v218, v152, v244
	v_sub_u32_e32 v219, v153, v244
	v_sub_f32_e32 v0, v140, v0
	v_sub_f32_e32 v146, v141, v146
	v_and_b32_e32 v147, 0x7fffffff, v146
	v_and_b32_e32 v146, 0x7fffffff, v0
	v_pk_mul_f32 v[156:157], v[228:229], v[146:147]
	v_cvt_f32_i32_e32 v0, v164
	v_cvt_f32_i32_e32 v146, v165
	v_sub_u32_e32 v220, v150, v244
	v_sub_u32_e32 v221, v151, v244
	v_sub_f32_e32 v0, v138, v0
	v_sub_f32_e32 v146, v139, v146
	v_and_b32_e32 v147, 0x7fffffff, v146
	v_and_b32_e32 v146, 0x7fffffff, v0
	v_pk_mul_f32 v[154:155], v[228:229], v[146:147]
	v_cvt_f32_i32_e32 v0, v166
	v_cvt_f32_i32_e32 v146, v167
	v_pk_mul_f32 v[160:161], v[228:229], v[148:149]
	v_cvt_f32_i32_e32 v162, v177
	v_sub_f32_e32 v0, v136, v0
	v_sub_f32_e32 v146, v137, v146
	v_and_b32_e32 v147, 0x7fffffff, v146
	v_and_b32_e32 v146, 0x7fffffff, v0
	v_pk_mul_f32 v[152:153], v[228:229], v[146:147]
	v_cvt_f32_i32_e32 v0, v168
	v_cvt_f32_i32_e32 v146, v169
	v_sub_f32_e32 v162, v143, v162
	v_and_b32_e32 v163, 0x7fffffff, v162
	v_sub_f32_e32 v0, v134, v0
	v_sub_f32_e32 v146, v135, v146
	v_and_b32_e32 v147, 0x7fffffff, v146
	v_and_b32_e32 v146, 0x7fffffff, v0
	v_pk_mul_f32 v[150:151], v[228:229], v[146:147]
	v_cvt_f32_i32_e32 v0, v170
	v_cvt_f32_i32_e32 v146, v171
	v_cvt_f32_i32_e32 v164, v175
	v_sub_f32_e32 v0, v132, v0
	v_sub_f32_e32 v146, v133, v146
	v_and_b32_e32 v147, 0x7fffffff, v146
	v_and_b32_e32 v146, 0x7fffffff, v0
	v_pk_mul_f32 v[148:149], v[228:229], v[146:147]
	v_cvt_f32_i32_e32 v0, v172
	v_cvt_f32_i32_e32 v146, v173
	v_sub_f32_e32 v164, v145, v164
	v_and_b32_e32 v165, 0x7fffffff, v164
	v_sub_f32_e32 v0, v130, v0
	v_sub_f32_e32 v146, v131, v146
	v_and_b32_e32 v147, 0x7fffffff, v146
	v_and_b32_e32 v146, 0x7fffffff, v0
	v_cvt_f32_i32_e32 v0, v176
	v_pk_mul_f32 v[146:147], v[230:231], v[146:147]
	v_sub_f32_e32 v0, v142, v0
	v_and_b32_e32 v162, 0x7fffffff, v0
	v_cvt_f32_i32_e32 v0, v174
	v_pk_mul_f32 v[174:175], v[228:229], v[162:163]
	v_cvt_f32_i32_e32 v162, v211
	v_sub_f32_e32 v0, v144, v0
	v_and_b32_e32 v164, 0x7fffffff, v0
	v_cvt_f32_i32_e32 v0, v210
	v_sub_f32_e32 v162, v141, v162
	v_and_b32_e32 v163, 0x7fffffff, v162
	v_pk_mul_f32 v[176:177], v[228:229], v[164:165]
	v_sub_f32_e32 v0, v140, v0
	v_and_b32_e32 v162, 0x7fffffff, v0
	v_pk_mul_f32 v[172:173], v[228:229], v[162:163]
	v_cvt_f32_i32_e32 v0, v212
	v_cvt_f32_i32_e32 v162, v213
	v_sub_f32_e32 v0, v138, v0
	v_sub_f32_e32 v162, v139, v162
	v_and_b32_e32 v163, 0x7fffffff, v162
	v_and_b32_e32 v162, 0x7fffffff, v0
	v_pk_mul_f32 v[170:171], v[228:229], v[162:163]
	v_cvt_f32_i32_e32 v0, v214
	v_cvt_f32_i32_e32 v162, v215
	v_sub_f32_e32 v0, v136, v0
	v_sub_f32_e32 v162, v137, v162
	v_and_b32_e32 v163, 0x7fffffff, v162
	v_and_b32_e32 v162, 0x7fffffff, v0
	v_pk_mul_f32 v[168:169], v[228:229], v[162:163]
	v_cvt_f32_i32_e32 v0, v216
	v_cvt_f32_i32_e32 v162, v217
	v_sub_f32_e32 v0, v134, v0
	v_sub_f32_e32 v162, v135, v162
	v_and_b32_e32 v163, 0x7fffffff, v162
	v_and_b32_e32 v162, 0x7fffffff, v0
	v_pk_mul_f32 v[166:167], v[228:229], v[162:163]
	v_cvt_f32_i32_e32 v0, v218
	v_cvt_f32_i32_e32 v162, v219
	v_sub_f32_e32 v0, v132, v0
	v_sub_f32_e32 v162, v133, v162
	v_and_b32_e32 v163, 0x7fffffff, v162
	v_and_b32_e32 v162, 0x7fffffff, v0
	v_pk_mul_f32 v[164:165], v[228:229], v[162:163]
	v_cvt_f32_i32_e32 v0, v220
	v_cvt_f32_i32_e32 v162, v221
	v_sub_f32_e32 v0, v130, v0
	v_sub_f32_e32 v162, v131, v162
	v_and_b32_e32 v163, 0x7fffffff, v162
	v_and_b32_e32 v162, 0x7fffffff, v0
	v_pk_mul_f32 v[162:163], v[230:231], v[162:163]
